# P0 x-row loop takes rows in reverse wave order (balances against the transpose item count)
# speedup vs baseline: 1.0073x; 1.0073x over previous
.LBB0_77:
	v_readlane_b32 s16, v252, 16
	v_readlane_b32 s26, v252, 26
	v_readlane_b32 s27, v252, 27
	v_readlane_b32 s30, v252, 30
	v_readlane_b32 s31, v252, 31
	s_cmpk_gt_i32 s13, 0x21ff
	s_mov_b64 s[62:63], s[26:27]
	s_mov_b64 s[66:67], s[30:31]
	v_readlane_b32 s17, v252, 17
	v_readlane_b32 s18, v252, 18
	v_readlane_b32 s19, v252, 19
	v_readlane_b32 s20, v252, 20
	v_readlane_b32 s21, v252, 21
	v_readlane_b32 s22, v252, 22
	v_readlane_b32 s23, v252, 23
	v_readlane_b32 s24, v252, 24
	v_readlane_b32 s25, v252, 25
	v_readlane_b32 s28, v252, 28
	v_readlane_b32 s29, v252, 29
	s_cbranch_scc1 .LBB0_84
	s_lshl_b32 s6, s96, 3
	s_sub_i32 s6, s6, 1
	s_sub_i32 s6, s6, s13
	s_lshl_b32 s6, s6, 1
	s_lshl_b32 s14, s96, 4
	s_ashr_i32 s7, s6, 31
	v_ashrrev_i32_e32 v1, 31, v0
	v_lshlrev_b32_e32 v2, 2, v38
	s_ashr_i32 s15, s14, 31
	s_lshl_b64 s[20:21], s[6:7], 11
	v_xor_b32_e32 v39, 4, v2
	v_xor_b32_e32 v40, 8, v2
	v_xor_b32_e32 v41, 16, v2
	v_xor_b32_e32 v42, 32, v2
	v_xor_b32_e32 v43, 64, v2
	v_xor_b32_e32 v44, 0x80, v2
	v_cmp_eq_u32_e64 s[0:1], 0, v38
	s_lshl_b64 s[16:17], s[6:7], 2
	s_lshl_b64 s[18:19], s[14:15], 2
	v_lshl_add_u64 v[32:33], v[0:1], 1, s[20:21]
	s_lshl_b64 s[20:21], s[14:15], 11
	v_lshlrev_b64 v[34:35], 2, v[0:1]
	v_mov_b32_e32 v45, 0x358637bd
	v_mov_b32_e32 v46, 0xec00000
	s_mov_b32 s24, 0x3800000
	s_branch .LBB0_80
